# gather_u: leaner row-fetch stage (pre-shifted list entries, v_and_or address, rotating list registers; 3 fewer VALU per row group)
# speedup vs baseline: 1.0050x; 1.0050x over previous
; __device__ void phase_gather_u(const Params& p) {
;   const int tid = threadIdx.x, lane = tid & 63, wid = tid >> 6;
;   unsigned char* ws = p.ws;
;   const unsigned char* ub = ws + OFF_XB;
;   const int* idxg = (const int*)(ws + OFF_IDX);
;   u32x4* xq = (u32x4*)(ws + OFF_XQ);
;   int* wbuf = (int*)(ws + OFF_WBUF);
;   float* sxa = (float*)(ws + OFF_WBUF + 8 * MIB);
;   const bool b5 = (lane & 32) != 0, b4 = (lane & 16) != 0, b3 = (lane & 8) != 0;
;   const int srcl = ((lane & 1) << 3) | (((lane >> 1) & 1) << 4) | (((lane >> 2) & 1) << 5);
;   const int tbase = blockIdx.x * 8 + wid, tstride = gridDim.x * 8;
;   for (int t = tbase; t < T_TOK; t += tstride) {
;     ...
;     for (int t = tbase; t < T_TOK; t += tstride) {
;       const u32x4 ph = xq[((size_t)t * 64 + lane) * 2], pl = xq[((size_t)t * 64 + lane) * 2 + 1];
;       const int idA = idxg[(size_t)t * 128 + lane], idB = idxg[(size_t)t * 128 + 64 + lane];
.LBB0_1205:
	s_or_b64 exec, exec, s[4:5]
	v_and_b32_e32 v0, 32, v139
	v_cmp_eq_u32_e64 s[2:3], 0, v0
	v_and_b32_e32 v0, 16, v139
	v_cmp_eq_u32_e64 s[4:5], 0, v0
	v_and_b32_e32 v0, 8, v139
	s_add_u32 s10, s34, 0xc000000
	v_cmp_eq_u32_e64 s[6:7], 0, v0
	v_mov_b32_e32 v1, 0
	v_lshlrev_b32_e32 v0, 5, v138
	s_addc_u32 s11, s35, 0
	s_waitcnt lgkmcnt(0)
	v_lshl_add_u64 v[2:3], s[34:35], 0, v[0:1]
	v_lshlrev_b32_e32 v0, 2, v138
	v_lshlrev_b32_e32 v82, 3, v139
	v_writelane_b32 v250, s10, 18
	v_mbcnt_hi_u32_b32 v83, -1, v30
	v_and_b32_e32 v4, 56, v82
	v_lshl_add_u64 v[76:77], s[10:11], 0, v[0:1]
	v_lshlrev_b32_e32 v0, 4, v138
	s_waitcnt vmcnt(0)
	v_lshl_add_u64 v[72:73], s[34:35], 0, v[0:1]
	v_and_b32_e32 v0, 64, v83
	s_add_u32 s70, s34, 0x17400000
	s_mov_b64 s[8:9], 0x15400000
	v_add_u32_e32 v84, 64, v0
	v_or_b32_e32 v0, v0, v4
	s_addc_u32 s71, s35, 0
	s_mov_b32 s33, 0
	v_lshl_add_u64 v[74:75], v[2:3], 0, s[8:9]
	v_writelane_b32 v250, s11, 19
	v_cmp_gt_u32_e64 s[8:9], 8, v138
	v_cmp_eq_u32_e64 s[10:11], 1, v138
	v_cmp_eq_u32_e64 s[12:13], 2, v138
	v_cmp_eq_u32_e64 s[14:15], 3, v138
	v_cmp_eq_u32_e64 s[16:17], 4, v138
	v_cmp_eq_u32_e64 s[18:19], 5, v138
	v_cmp_eq_u32_e64 s[20:21], 6, v138
	v_cmp_eq_u32_e64 s[22:23], 7, v138
	s_movk_i32 s48, 0x3fff
	v_xor_b32_e32 v89, 32, v83
	v_xor_b32_e32 v90, 16, v83
	v_xor_b32_e32 v88, 8, v83
	v_xor_b32_e32 v87, 4, v83
	v_xor_b32_e32 v86, 2, v83
	v_xor_b32_e32 v85, 1, v83
	v_lshlrev_b32_e32 v91, 2, v0
	v_and_b32_e32 v96, 15, v138
	v_lshrrev_b32_e32 v99, 4, v138
	v_lshlrev_b32_e32 v98, 2, v138
	v_lshrrev_b32_e32 v100, 6, v139
	v_cmp_eq_u32_e64 s[8:9], 0, v96
	v_lshlrev_b32_e32 v97, 5, v96
	v_lshlrev_b32_e32 v96, 4, v96
	v_readfirstlane_b32 s60, v100
	v_readfirstlane_b32 s61, v112
	s_add_u32 s64, s34, 0x15400000
	s_addc_u32 s65, s35, 0
	s_add_u32 s62, s34, 0xc000000
	s_addc_u32 s63, s35, 0
	s_lshl_b32 s60, s60, 10
	s_and_saveexec_b64 s[38:39], s[0:1]
	s_cbranch_execz .Lgu_done
	s_mov_b32 s33, 0
	s_mov_b32 s66, 0
	s_lshl_b32 s40, s61, 9
	s_add_u32 s40, s62, s40
	s_addc_u32 s41, s63, 0
	s_lshl_b32 s46, s61, 11
	s_add_u32 s46, s64, s46
	s_addc_u32 s47, s65, 0
	global_load_dword v94, v98, s[40:41]
	global_load_dword v95, v98, s[40:41] offset:256
	global_load_dwordx4 v[168:171], v97, s[46:47]
	global_load_dwordx4 v[172:175], v97, s[46:47] offset:16
	global_load_dwordx4 v[176:179], v97, s[46:47] offset:512
	global_load_dwordx4 v[180:183], v97, s[46:47] offset:528
	global_load_dwordx4 v[184:187], v97, s[46:47] offset:1024
	global_load_dwordx4 v[188:191], v97, s[46:47] offset:1040
	global_load_dwordx4 v[192:195], v97, s[46:47] offset:1536
	global_load_dwordx4 v[196:199], v97, s[46:47] offset:1552
	s_add_i32 s37, s61, s68
	s_lshl_b32 s40, s37, 9
	s_add_u32 s40, s62, s40
	s_addc_u32 s41, s63, 0
	s_lshl_b32 s46, s37, 11
	s_add_u32 s46, s64, s46
	s_addc_u32 s47, s65, 0
	global_load_dword v232, v98, s[40:41]
	global_load_dword v233, v98, s[40:41] offset:256
	global_load_dwordx4 v[200:203], v97, s[46:47]
	global_load_dwordx4 v[204:207], v97, s[46:47] offset:16
	global_load_dwordx4 v[208:211], v97, s[46:47] offset:512
	global_load_dwordx4 v[212:215], v97, s[46:47] offset:528
	global_load_dwordx4 v[216:219], v97, s[46:47] offset:1024
	global_load_dwordx4 v[220:223], v97, s[46:47] offset:1040
	global_load_dwordx4 v[224:227], v97, s[46:47] offset:1536
	global_load_dwordx4 v[228:231], v97, s[46:47] offset:1552
	s_mov_b32 s67, 0xfffffc00

; __device__ void phase_gather_u(const Params& p) {
;     ...
;       const int idA = idxg[(size_t)t * 128 + lane], idB = idxg[(size_t)t * 128 + 64 + lane];
;       unsigned long long m0 = __ballot((idA >> 12) == r), m1 = __ballot((idB >> 12) == r);
;       while (m0 | m1) {
;         int jk[16];
;         u32x4 rw[16];
;         const int nvalid = min((int)(__popcll(m0) + __popcll(m1)), 16);
;         int jfirst, efirst;
;         if (m0) { jfirst = __builtin_amdgcn_readfirstlane(__ffsll((long long)m0) - 1); efirst = __builtin_amdgcn_readlane(idA, jfirst); }
;         else { const int j1 = __builtin_amdgcn_readfirstlane(__ffsll((long long)m1) - 1); efirst = __builtin_amdgcn_readlane(idB, j1); jfirst = 64 + j1; }
; #pragma unroll
;         for (int k = 0; k < 16; ++k) {
;           int j = jfirst, e = efirst;
;           if (m0) { const int jj = __builtin_amdgcn_readfirstlane(__ffsll((long long)m0) - 1); m0 &= m0 - 1ull; j = jj; e = __builtin_amdgcn_readlane(idA, jj); }
;           else if (m1) { const int jj = __builtin_amdgcn_readfirstlane(__ffsll((long long)m1) - 1); m1 &= m1 - 1ull; j = 64 + jj; e = __builtin_amdgcn_readlane(idB, jj); }
;           jk[k] = j;
;           rw[k] = *(const u32x4*)(ub + (size_t)e * 1024 + lane * 16);
.Lgu_cpdone:
	v_lshrrev_b32_e32 v103, 12, v92
	v_lshrrev_b32_e32 v104, 12, v93
	v_cmp_eq_u32_e64 s[44:45], s33, v103
	v_cmp_eq_u32_e64 s[42:43], s33, v104
	s_nop 3
	s_bcnt1_i32_b64 s59, s[44:45]
	s_bcnt1_i32_b64 s56, s[42:43]
	s_add_i32 s56, s56, s59
	s_cmp_eq_u32 s56, 0
	s_cbranch_scc1 .Lgu_tnext
	v_mbcnt_lo_u32_b32 v114, s44, 0
	v_mbcnt_hi_u32_b32 v114, s45, v114
	v_mbcnt_lo_u32_b32 v111, s42, 0
	v_mbcnt_hi_u32_b32 v111, s43, v111
	v_lshl_add_u32 v113, v92, 10, v98
	v_lshl_add_u32 v100, v114, 2, s60
	v_add_u32_e32 v111, s59, v111
	s_mov_b64 exec, s[44:45]
	ds_write_b32 v100, v113
	s_mov_b64 exec, -1
	v_add_u32_e32 v113, 0x100, v98
	v_lshl_add_u32 v100, v111, 2, s60
	v_lshl_add_u32 v113, v93, 10, v113
	s_mov_b64 exec, s[42:43]
	ds_write_b32 v100, v113
	s_mov_b64 exec, -1
	s_add_i32 s57, s56, 3
	s_lshr_b32 s57, s57, 2
	v_lshl_add_u32 v101, v99, 2, s60
	v_mov_b32_e32 v102, v99
	s_mov_b32 s58, 0
	ds_read_b32 v115, v101
	v_add_u32_e32 v101, 16, v101
	s_waitcnt lgkmcnt(0)
	ds_read_b32 v116, v101
	v_cmp_gt_u32_e64 s[50:51], s56, v102
	v_add_u32_e32 v101, 16, v101
	v_add_u32_e32 v102, 4, v102
	s_nop 0
	v_cndmask_b32_e64 v103, 0, v115, s[50:51]
	v_and_or_b32 v104, v103, s67, v96
	v_and_b32_e32 v105, 0x3ff, v103
	s_and_b64 s[50:51], s[50:51], s[8:9]
	global_load_dwordx4 v[32:35], v104, s[34:35]
	global_load_dwordx4 v[36:39], v104, s[34:35] offset:256
	global_load_dwordx4 v[40:43], v104, s[34:35] offset:512
	global_load_dwordx4 v[44:47], v104, s[34:35] offset:768
	s_waitcnt lgkmcnt(0)
	ds_read_b32 v117, v101
	v_cmp_gt_u32_e64 s[52:53], s56, v102
	v_add_u32_e32 v101, 16, v101
	v_add_u32_e32 v102, 4, v102
	s_nop 0
	v_cndmask_b32_e64 v103, 0, v116, s[52:53]
	v_and_or_b32 v104, v103, s67, v96
	v_and_b32_e32 v106, 0x3ff, v103
	s_and_b64 s[52:53], s[52:53], s[8:9]
	global_load_dwordx4 v[48:51], v104, s[34:35]
	global_load_dwordx4 v[52:55], v104, s[34:35] offset:256
	global_load_dwordx4 v[56:59], v104, s[34:35] offset:512
	global_load_dwordx4 v[60:63], v104, s[34:35] offset:768
; __device__ void phase_gather_u(const Params& p) {
;     ...
; #pragma unroll
;         for (int k = 0; k < 16; ++k) {
;           int j = jfirst, e = efirst;
;           if (m0) { const int jj = __builtin_amdgcn_readfirstlane(__ffsll((long long)m0) - 1); m0 &= m0 - 1ull; j = jj; e = __builtin_amdgcn_readlane(idA, jj); }
;           else if (m1) { const int jj = __builtin_amdgcn_readfirstlane(__ffsll((long long)m1) - 1); m1 &= m1 - 1ull; j = 64 + jj; e = __builtin_amdgcn_readlane(idB, jj); }
;           jk[k] = j;
;           rw[k] = *(const u32x4*)(ub + (size_t)e * 1024 + lane * 16);
;         }
; #pragma unroll
;         for (int bt = 0; bt < 2; ++bt) {
;           int dv[8];
; #pragma unroll
;           for (int k = 0; k < 8; ++k) {
;             int dh = 0, dl = 0;
; #pragma unroll
;             for (int q = 0; q < 4; ++q) {
;               dh = __builtin_amdgcn_sdot8((int)rw[bt * 8 + k][q], (int)ph[q], dh, false);
;               dl = __builtin_amdgcn_sdot8((int)rw[bt * 8 + k][q], (int)pl[q], dl, false);
;             }
;             dv[k] = 16 * dh + dl;
;           }
;           int a4[4], a2[2];
; #pragma unroll
;           for (int k = 0; k < 4; ++k) {
;             const int mine = b5 ? dv[k + 4] : dv[k], oth = b5 ? dv[k] : dv[k + 4];
;             a4[k] = mine + __shfl_xor(oth, 32);
;           }
; #pragma unroll
;           for (int k = 0; k < 2; ++k) {
;             const int mine = b4 ? a4[k + 2] : a4[k], oth = b4 ? a4[k] : a4[k + 2];
;             a2[k] = mine + __shfl_xor(oth, 16);
;           }
;           int c1;
;           {
;             const int mine = b3 ? a2[1] : a2[0], oth = b3 ? a2[0] : a2[1];
;             c1 = mine + __shfl_xor(oth, 8);
;           }
;           c1 += __shfl_xor(c1, 4);
;           c1 += __shfl_xor(c1, 2);
;           c1 += __shfl_xor(c1, 1);
;           const int val = __shfl(c1, srcl);
;           int jsel = jk[bt * 8];
; #pragma unroll
;           for (int k = 1; k < 8; ++k) jsel = (lane == k) ? jk[bt * 8 + k] : jsel;
;           if (lane < 8 && lane < nvalid - bt * 8) wbuf[(size_t)t * 128 + jsel] = val;
.Lgu_gloop:
	s_waitcnt lgkmcnt(0)
	ds_read_b32 v115, v101
	v_cmp_gt_u32_e64 s[54:55], s56, v102
	v_add_u32_e32 v101, 16, v101
	v_add_u32_e32 v102, 4, v102
	s_nop 0
	v_cndmask_b32_e64 v103, 0, v117, s[54:55]
	v_and_or_b32 v104, v103, s67, v96
	v_and_b32_e32 v107, 0x3ff, v103
	s_and_b64 s[54:55], s[54:55], s[8:9]
	global_load_dwordx4 v[144:147], v104, s[34:35]
	global_load_dwordx4 v[148:151], v104, s[34:35] offset:256
	global_load_dwordx4 v[152:155], v104, s[34:35] offset:512
	global_load_dwordx4 v[156:159], v104, s[34:35] offset:768
	s_waitcnt vmcnt(8)
	v_mov_b32_e32 v108, 0
	v_mov_b32_e32 v109, 0
	s_nop 1
	v_dot8c_i32_i4_e32 v108, v32, v0
	v_dot8c_i32_i4_e32 v109, v32, v4
	v_dot8c_i32_i4_e32 v108, v33, v1
	v_dot8c_i32_i4_e32 v109, v33, v5
	v_dot8c_i32_i4_e32 v108, v34, v2
	v_dot8c_i32_i4_e32 v109, v34, v6
	v_dot8c_i32_i4_e32 v108, v35, v3
	v_dot8c_i32_i4_e32 v109, v35, v7
	v_dot8c_i32_i4_e32 v108, v36, v8
	v_dot8c_i32_i4_e32 v109, v36, v12
	v_dot8c_i32_i4_e32 v108, v37, v9
	v_dot8c_i32_i4_e32 v109, v37, v13
	v_dot8c_i32_i4_e32 v108, v38, v10
	v_dot8c_i32_i4_e32 v109, v38, v14
	v_dot8c_i32_i4_e32 v108, v39, v11
	v_dot8c_i32_i4_e32 v109, v39, v15
	v_dot8c_i32_i4_e32 v108, v40, v16
	v_dot8c_i32_i4_e32 v109, v40, v20
	v_dot8c_i32_i4_e32 v108, v41, v17
	v_dot8c_i32_i4_e32 v109, v41, v21
	v_dot8c_i32_i4_e32 v108, v42, v18
	v_dot8c_i32_i4_e32 v109, v42, v22
	v_dot8c_i32_i4_e32 v108, v43, v19
	v_dot8c_i32_i4_e32 v109, v43, v23
	v_dot8c_i32_i4_e32 v108, v44, v24
	v_dot8c_i32_i4_e32 v109, v44, v28
	v_dot8c_i32_i4_e32 v108, v45, v25
	v_dot8c_i32_i4_e32 v109, v45, v29
	v_dot8c_i32_i4_e32 v108, v46, v26
	v_dot8c_i32_i4_e32 v109, v46, v30
	v_dot8c_i32_i4_e32 v108, v47, v27
	v_dot8c_i32_i4_e32 v109, v47, v31
	s_nop 2
	v_lshl_add_u32 v110, v108, 4, v109
	s_nop 1
	v_add_u32_dpp v110, v110, v110 quad_perm:[1,0,3,2] row_mask:0xf bank_mask:0xf
	s_nop 1
	v_add_u32_dpp v110, v110, v110 quad_perm:[2,3,0,1] row_mask:0xf bank_mask:0xf
	s_nop 1
	v_add_u32_dpp v110, v110, v110 row_half_mirror row_mask:0xf bank_mask:0xf
	s_nop 1
	v_add_u32_dpp v110, v110, v110 row_mirror row_mask:0xf bank_mask:0xf
	s_mov_b64 exec, s[50:51]
	global_store_dword v105, v110, s[48:49]
	s_mov_b64 exec, -1
	s_add_i32 s58, s58, 1
	s_cmp_ge_u32 s58, s57
	s_cbranch_scc1 .Lgu_tnext
	s_waitcnt lgkmcnt(0)
	ds_read_b32 v116, v101
	v_cmp_gt_u32_e64 s[50:51], s56, v102
	v_add_u32_e32 v101, 16, v101
	v_add_u32_e32 v102, 4, v102
	s_nop 0
	v_cndmask_b32_e64 v103, 0, v115, s[50:51]
	v_and_or_b32 v104, v103, s67, v96
	v_and_b32_e32 v105, 0x3ff, v103
	s_and_b64 s[50:51], s[50:51], s[8:9]
	global_load_dwordx4 v[32:35], v104, s[34:35]
	global_load_dwordx4 v[36:39], v104, s[34:35] offset:256
	global_load_dwordx4 v[40:43], v104, s[34:35] offset:512
	global_load_dwordx4 v[44:47], v104, s[34:35] offset:768
	s_waitcnt vmcnt(8)
	v_mov_b32_e32 v108, 0
	v_mov_b32_e32 v109, 0
	s_nop 1
	v_dot8c_i32_i4_e32 v108, v48, v0
	v_dot8c_i32_i4_e32 v109, v48, v4
	v_dot8c_i32_i4_e32 v108, v49, v1
	v_dot8c_i32_i4_e32 v109, v49, v5
	v_dot8c_i32_i4_e32 v108, v50, v2
	v_dot8c_i32_i4_e32 v109, v50, v6
	v_dot8c_i32_i4_e32 v108, v51, v3
	v_dot8c_i32_i4_e32 v109, v51, v7
	v_dot8c_i32_i4_e32 v108, v52, v8
	v_dot8c_i32_i4_e32 v109, v52, v12
	v_dot8c_i32_i4_e32 v108, v53, v9
	v_dot8c_i32_i4_e32 v109, v53, v13
	v_dot8c_i32_i4_e32 v108, v54, v10
	v_dot8c_i32_i4_e32 v109, v54, v14
	v_dot8c_i32_i4_e32 v108, v55, v11
	v_dot8c_i32_i4_e32 v109, v55, v15
	v_dot8c_i32_i4_e32 v108, v56, v16
	v_dot8c_i32_i4_e32 v109, v56, v20
	v_dot8c_i32_i4_e32 v108, v57, v17
	v_dot8c_i32_i4_e32 v109, v57, v21
	v_dot8c_i32_i4_e32 v108, v58, v18
	v_dot8c_i32_i4_e32 v109, v58, v22
	v_dot8c_i32_i4_e32 v108, v59, v19
	v_dot8c_i32_i4_e32 v109, v59, v23
	v_dot8c_i32_i4_e32 v108, v60, v24
	v_dot8c_i32_i4_e32 v109, v60, v28
	v_dot8c_i32_i4_e32 v108, v61, v25
	v_dot8c_i32_i4_e32 v109, v61, v29
	v_dot8c_i32_i4_e32 v108, v62, v26
	v_dot8c_i32_i4_e32 v109, v62, v30
	v_dot8c_i32_i4_e32 v108, v63, v27
	v_dot8c_i32_i4_e32 v109, v63, v31
	s_nop 2
	v_lshl_add_u32 v110, v108, 4, v109
	s_nop 1
	v_add_u32_dpp v110, v110, v110 quad_perm:[1,0,3,2] row_mask:0xf bank_mask:0xf
	s_nop 1
	v_add_u32_dpp v110, v110, v110 quad_perm:[2,3,0,1] row_mask:0xf bank_mask:0xf
	s_nop 1
	v_add_u32_dpp v110, v110, v110 row_half_mirror row_mask:0xf bank_mask:0xf
	s_nop 1
	v_add_u32_dpp v110, v110, v110 row_mirror row_mask:0xf bank_mask:0xf
	s_mov_b64 exec, s[52:53]
	global_store_dword v106, v110, s[48:49]
	s_mov_b64 exec, -1
	s_add_i32 s58, s58, 1
	s_cmp_ge_u32 s58, s57
	s_cbranch_scc1 .Lgu_tnext
	s_waitcnt lgkmcnt(0)
	ds_read_b32 v117, v101
	v_cmp_gt_u32_e64 s[52:53], s56, v102
	v_add_u32_e32 v101, 16, v101
	v_add_u32_e32 v102, 4, v102
	s_nop 0
	v_cndmask_b32_e64 v103, 0, v116, s[52:53]
	v_and_or_b32 v104, v103, s67, v96
	v_and_b32_e32 v106, 0x3ff, v103
	s_and_b64 s[52:53], s[52:53], s[8:9]
	global_load_dwordx4 v[48:51], v104, s[34:35]
	global_load_dwordx4 v[52:55], v104, s[34:35] offset:256
	global_load_dwordx4 v[56:59], v104, s[34:35] offset:512
	global_load_dwordx4 v[60:63], v104, s[34:35] offset:768
	s_waitcnt vmcnt(8)
	v_mov_b32_e32 v108, 0
	v_mov_b32_e32 v109, 0
	s_nop 1
	v_dot8c_i32_i4_e32 v108, v144, v0
	v_dot8c_i32_i4_e32 v109, v144, v4
	v_dot8c_i32_i4_e32 v108, v145, v1
	v_dot8c_i32_i4_e32 v109, v145, v5
	v_dot8c_i32_i4_e32 v108, v146, v2
	v_dot8c_i32_i4_e32 v109, v146, v6
	v_dot8c_i32_i4_e32 v108, v147, v3
	v_dot8c_i32_i4_e32 v109, v147, v7
	v_dot8c_i32_i4_e32 v108, v148, v8
	v_dot8c_i32_i4_e32 v109, v148, v12
	v_dot8c_i32_i4_e32 v108, v149, v9
	v_dot8c_i32_i4_e32 v109, v149, v13
	v_dot8c_i32_i4_e32 v108, v150, v10
	v_dot8c_i32_i4_e32 v109, v150, v14
	v_dot8c_i32_i4_e32 v108, v151, v11
	v_dot8c_i32_i4_e32 v109, v151, v15
	v_dot8c_i32_i4_e32 v108, v152, v16
	v_dot8c_i32_i4_e32 v109, v152, v20
	v_dot8c_i32_i4_e32 v108, v153, v17
	v_dot8c_i32_i4_e32 v109, v153, v21
	v_dot8c_i32_i4_e32 v108, v154, v18
	v_dot8c_i32_i4_e32 v109, v154, v22
	v_dot8c_i32_i4_e32 v108, v155, v19
	v_dot8c_i32_i4_e32 v109, v155, v23
	v_dot8c_i32_i4_e32 v108, v156, v24
	v_dot8c_i32_i4_e32 v109, v156, v28
	v_dot8c_i32_i4_e32 v108, v157, v25
	v_dot8c_i32_i4_e32 v109, v157, v29
	v_dot8c_i32_i4_e32 v108, v158, v26
	v_dot8c_i32_i4_e32 v109, v158, v30
	v_dot8c_i32_i4_e32 v108, v159, v27
	v_dot8c_i32_i4_e32 v109, v159, v31
	s_nop 2
	v_lshl_add_u32 v110, v108, 4, v109
	s_nop 1
	v_add_u32_dpp v110, v110, v110 quad_perm:[1,0,3,2] row_mask:0xf bank_mask:0xf
	s_nop 1
	v_add_u32_dpp v110, v110, v110 quad_perm:[2,3,0,1] row_mask:0xf bank_mask:0xf
	s_nop 1
	v_add_u32_dpp v110, v110, v110 row_half_mirror row_mask:0xf bank_mask:0xf
	s_nop 1
	v_add_u32_dpp v110, v110, v110 row_mirror row_mask:0xf bank_mask:0xf
	s_mov_b64 exec, s[54:55]
	global_store_dword v107, v110, s[48:49]
	s_mov_b64 exec, -1
	s_add_i32 s58, s58, 1
	s_cmp_lt_u32 s58, s57
	s_cbranch_scc1 .Lgu_gloop
